# selected-loop back-edge rotation: per-tile barrier moved to the head of the next iteration's path, scalar dispatch runs before it
# baseline (speedup 1.0000x reference)
; #define ISSUE_TILE(RK, RV, T, LDV)                                                   \
;   {                                                                                  \
;     pk0 = BLOAD(RK, koff, (T)*8192);                                                 \
;     pv0 = BLOAD(RV, ((LDV) == 512) ? voffc : voffs, (T)*128);                        \
;   }
; DI void nsa_item(int wv0, PP p, int item, unsigned char* smem) {
;     ...
;         if (j2 >= 0) COMMIT_BUF(bn2)
;         __syncthreads();
;         jc = j1;
;         j1 = j2;
;         bc = bn;
;         if (j1 >= 0) {
;           j2 = next_bit(blo, bhi, j1 + 1);
;           if (j2 >= 0) ISSUE_TILE(rK, rV, j2, S_)
;         } else {
;           j2 = -1;
;         }
; #pragma unroll
;         for (int a = 0; a < 2; ++a)
; #pragma unroll
;           for (int c = 0; c < 4; ++c) sc_[a][c] = sn_[a][c];
;       }
.Lmy_selC_old:
	s_barrier
	v_sub_co_u32_e64 v2, s[36:37], s42, 64
	s_cmp_eq_u32 s32, 0
	s_cbranch_scc1 .Lmy_selC_old2
	v_mov_b64_e32 v[108:109], v[96:97]
	v_mov_b64_e32 v[112:113], v[92:93]
	v_mov_b64_e32 v[116:117], v[88:89]
	v_mov_b64_e32 v[128:129], v[84:85]
	v_mov_b64_e32 v[124:125], v[80:81]
	v_mov_b64_e32 v[120:121], v[76:77]
	v_mov_b64_e32 v[104:105], v[72:73]
	v_mov_b64_e32 v[100:101], v[68:69]
	v_mov_b64_e32 v[106:107], v[94:95]
	v_mov_b64_e32 v[110:111], v[90:91]
	v_mov_b64_e32 v[114:115], v[86:87]
	v_mov_b64_e32 v[126:127], v[82:83]
	v_mov_b64_e32 v[122:123], v[78:79]
	v_mov_b64_e32 v[118:119], v[74:75]
	v_mov_b64_e32 v[102:103], v[70:71]
	v_mov_b64_e32 v[98:99], v[66:67]

; #define ISSUE_TILE(RK, RV, T, LDV)                                                   \
;   {                                                                                  \
;     pk0 = BLOAD(RK, koff, (T)*8192);                                                 \
;     pv0 = BLOAD(RV, ((LDV) == 512) ? voffc : voffs, (T)*128);                        \
;   }
; DI void nsa_item(int wv0, PP p, int item, unsigned char* smem) {
;     ...
;         if (j2 >= 0) COMMIT_BUF(bn2)
;         __syncthreads();
;         jc = j1;
;         j1 = j2;
;         bc = bn;
;         if (j1 >= 0) {
;           j2 = next_bit(blo, bhi, j1 + 1);
;           if (j2 >= 0) ISSUE_TILE(rK, rV, j2, S_)
;         } else {
;           j2 = -1;
;         }
; #pragma unroll
;         for (int a = 0; a < 2; ++a)
; #pragma unroll
;           for (int c = 0; c < 4; ++c) sc_[a][c] = sn_[a][c];
;       }
.Lmy_tail_bar:
	s_waitcnt lgkmcnt(0)
	s_and_b64 vcc, exec, s[38:39]
	s_cbranch_vccz .LBB0_878
	s_barrier
	s_branch .LBB0_899
.Lmy_selC_old882:
	s_barrier
	s_cmp_eq_u32 s32, 0
	s_cbranch_scc1 .LBB0_882
	v_mov_b64_e32 v[108:109], v[96:97]
	v_mov_b64_e32 v[112:113], v[92:93]
	v_mov_b64_e32 v[116:117], v[88:89]
	v_mov_b64_e32 v[128:129], v[84:85]
	v_mov_b64_e32 v[124:125], v[80:81]
	v_mov_b64_e32 v[120:121], v[76:77]
	v_mov_b64_e32 v[104:105], v[72:73]
	v_mov_b64_e32 v[100:101], v[68:69]
	v_mov_b64_e32 v[106:107], v[94:95]
	v_mov_b64_e32 v[110:111], v[90:91]
	v_mov_b64_e32 v[114:115], v[86:87]
	v_mov_b64_e32 v[126:127], v[82:83]
	v_mov_b64_e32 v[122:123], v[78:79]
	v_mov_b64_e32 v[118:119], v[74:75]
	v_mov_b64_e32 v[102:103], v[70:71]
	v_mov_b64_e32 v[98:99], v[66:67]
	s_branch .LBB0_882

; DI f32x4 mfma16(bf16x8 a, bf16x8 b, f32x4 c) { return __builtin_amdgcn_mfma_f32_16x16x32_bf16(a, b, c, 0, 0, 0); }
; DI void flash_s3(const u16* sK, const bf16x8 (&qf)[2][2], float si0, float si1, f32x4 (&s)[2][4], int lane) {
;   const int l15 = lane & 15, lg = lane >> 4;
;   bf16x8 kf[4][2];
; #pragma unroll
;   for (int kt = 0; kt < 4; ++kt)
; #pragma unroll
;     for (int ks = 0; ks < 2; ++ks) kf[kt][ks] = *(const bf16x8*)(sK + (16 * kt + l15) * 72 + ks * 32 + lg * 8);
; #pragma unroll
;   for (int qt = 0; qt < 2; ++qt) {
;     const float si = qt ? si1 : si0;
; #pragma unroll
;     for (int kt = 0; kt < 4; ++kt) {
;       s[qt][kt] = f32x4{si, si, si, si};
; #pragma unroll
;       for (int ks = 0; ks < 2; ++ks) s[qt][kt] = mfma16(kf[kt][ks], qf[qt][ks], s[qt][kt]);
;     }
;   }
; }
; template <bool MASKED, class MaskF>
; DI void flash_pv3(const u16* sV, const f32x4 (&s)[2][4], f32x4 (&O)[2][4], float (&l)[2], MaskF ok, int lane) {
;   const int l15 = lane & 15, lg = lane >> 4;
;   union PFrag { unsigned u[4]; bf16x8 v; };
;   PFrag pf[2][2];
; #pragma unroll
;   for (int qt = 0; qt < 2; ++qt) {
;     float pr[4][4];
;     float rs = 0.f;
; #pragma unroll
;     for (int kt = 0; kt < 4; ++kt)
; #pragma unroll
;       for (int i = 0; i < 4; ++i) {
;         float pv = __builtin_amdgcn_exp2f(s[qt][kt][i]);
;         if (MASKED) pv = ok(kt, i) ? pv : 0.f;
;         pr[kt][i] = pv;
;         rs += pv;
;       }
;     l[qt] += rs;
; #pragma unroll
;     for (int ks2 = 0; ks2 < 2; ++ks2) {
;       pf[qt][ks2].u[0] = pk2(pr[2 * ks2][0], pr[2 * ks2][1]);
;       pf[qt][ks2].u[1] = pk2(pr[2 * ks2][2], pr[2 * ks2][3]);
;       pf[qt][ks2].u[2] = pk2(pr[2 * ks2 + 1][0], pr[2 * ks2 + 1][1]);
;       pf[qt][ks2].u[3] = pk2(pr[2 * ks2 + 1][2], pr[2 * ks2 + 1][3]);
;     }
;   }
; #pragma unroll
;   for (int ks2 = 0; ks2 < 2; ++ks2) {
; #pragma unroll
;     for (int dt = 0; dt < 4; ++dt) {
;       union { uint2 h[2]; bf16x8 v; } vf;
;       vf.h[0] = *(const uint2*)(sV + (16 * dt + l15) * 72 + 32 * ks2 + 4 * lg);
;       vf.h[1] = *(const uint2*)(sV + (16 * dt + l15) * 72 + 32 * ks2 + 16 + 4 * lg);
;       O[0][dt] = mfma16(vf.v, pf[0][ks2].v, O[0][dt]);
;       O[1][dt] = mfma16(vf.v, pf[1][ks2].v, O[1][dt]);
;     }
;   }
.Lmy_selC_fastA:
	s_barrier
	v_lshrrev_b64 v[186:187], s42, v[20:21]
	v_lshrrev_b64 v[2:3], s42, v[22:23]
	s_cmp_lt_u32 s42, 64
	s_cselect_b64 s[36:37], -1, 0
	v_cndmask_b32_e64 v0, v2, v186, s[36:37]
	v_and_b32_e32 v0, 1, v0
	s_mul_i32 s36, s44, 0x4800
	v_cmp_eq_u32_e32 vcc, 1, v0
	v_add_u32_e32 v0, s36, v158
	v_lshl_add_u32 v2, v28, 1, v0
	ds_read_b128 v[82:85], v2
	ds_read_b128 v[86:89], v2 offset:64
	s_cmp_eq_u32 s42, s33
	ds_read_b128 v[90:93], v2 offset:2304
	ds_read_b128 v[94:97], v2 offset:2368
	s_cselect_b64 s[36:37], -1, 0
	s_or_b64 s[36:37], vcc, s[36:37]
	v_cndmask_b32_e64 v78, v148, -v29, s[36:37]
	v_lshl_add_u32 v0, v164, 1, v0
	v_cndmask_b32_e64 v182, v148, -v161, s[36:37]
	ds_read_b128 v[166:169], v2 offset:4608
	ds_read_b128 v[170:173], v2 offset:4672
	ds_read_b128 v[174:177], v0
	ds_read_b128 v[178:181], v0 offset:64
	v_mov_b32_e32 v79, v78
	v_mov_b32_e32 v80, v78
	v_mov_b32_e32 v81, v78
	v_mov_b32_e32 v183, v182
	v_mov_b32_e32 v184, v182
	v_mov_b32_e32 v185, v182
	s_mulk_i32 s45, 0x4800
	v_lshlrev_b32_e32 v160, 1, v28
	v_lshlrev_b32_e32 v3, 1, v164
	s_add_i32 s40, s45, 32
	v_add3_u32 v198, s40, v160, v159
	v_add3_u32 v206, s40, v3, v159
	v_add_u32_e32 v214, 0x2000, v198
	v_add_u32_e32 v215, 0x2800, v198
	v_add_u32_e32 v216, 0x3000, v198
	v_add_u32_e32 v217, 0x2000, v206
	v_exp_f32_e32 v98, v98
	v_exp_f32_e32 v99, v99
	v_exp_f32_e32 v100, v100
	v_exp_f32_e32 v101, v101
	v_exp_f32_e32 v102, v102
	v_exp_f32_e32 v103, v103
	s_waitcnt lgkmcnt(7)
	v_mfma_f32_16x16x32_bf16 v[66:69], v[82:85], v[4:7], v[78:81]
	v_exp_f32_e32 v104, v104
	v_mfma_f32_16x16x32_bf16 v[82:85], v[82:85], v[12:15], v[182:185]
	v_exp_f32_e32 v105, v105
	s_waitcnt lgkmcnt(6)
	v_mfma_f32_16x16x32_bf16 v[66:69], v[86:89], v[8:11], v[66:69]
	ds_read_b64 v[198:199], v214 offset:1024
	ds_read_b64 v[200:201], v214 offset:1056
	ds_read_b64 v[202:203], v215 offset:1280
	ds_read_b64 v[204:205], v215 offset:1312
	ds_read_b64 v[206:207], v216 offset:1536
	ds_read_b64 v[208:209], v216 offset:1568
	ds_read_b64 v[210:211], v217 offset:1024
	ds_read_b64 v[212:213], v217 offset:1056
	v_exp_f32_e32 v118, v118
	v_exp_f32_e32 v119, v119
	s_waitcnt lgkmcnt(13)
	v_mfma_f32_16x16x32_bf16 v[70:73], v[90:93], v[4:7], v[78:81]
	v_exp_f32_e32 v120, v120
	v_mfma_f32_16x16x32_bf16 v[82:85], v[86:89], v[16:19], v[82:85]
	v_exp_f32_e32 v121, v121
	v_mfma_f32_16x16x32_bf16 v[86:89], v[90:93], v[12:15], v[182:185]
	v_exp_f32_e32 v122, v122
	v_exp_f32_e32 v123, v123
	s_waitcnt lgkmcnt(12)
	v_mfma_f32_16x16x32_bf16 v[70:73], v[94:97], v[8:11], v[70:73]
	v_exp_f32_e32 v124, v124
	v_exp_f32_e32 v125, v125
	s_waitcnt lgkmcnt(11)
	v_mfma_f32_16x16x32_bf16 v[74:77], v[166:169], v[4:7], v[78:81]
	v_exp_f32_e32 v126, v126
	v_exp_f32_e32 v127, v127
	s_waitcnt lgkmcnt(9)
	v_mfma_f32_16x16x32_bf16 v[78:81], v[174:177], v[4:7], v[78:81]
	v_exp_f32_e32 v128, v128
	v_mfma_f32_16x16x32_bf16 v[86:89], v[94:97], v[16:19], v[86:89]
	v_exp_f32_e32 v129, v129
	v_mfma_f32_16x16x32_bf16 v[90:93], v[166:169], v[12:15], v[182:185]
	v_exp_f32_e32 v114, v114
	v_mfma_f32_16x16x32_bf16 v[94:97], v[174:177], v[12:15], v[182:185]
	v_exp_f32_e32 v115, v115
	v_mfma_f32_16x16x32_bf16 v[74:77], v[170:173], v[8:11], v[74:77]
	v_exp_f32_e32 v116, v116
	v_exp_f32_e32 v117, v117
	s_waitcnt lgkmcnt(8)
	v_mfma_f32_16x16x32_bf16 v[78:81], v[178:181], v[8:11], v[78:81]
	v_exp_f32_e32 v110, v110
	v_exp_f32_e32 v111, v111
	v_mfma_f32_16x16x32_bf16 v[90:93], v[170:173], v[16:19], v[90:93]
	v_exp_f32_e32 v112, v112
	v_exp_f32_e32 v113, v113
	v_mfma_f32_16x16x32_bf16 v[94:97], v[178:181], v[16:19], v[94:97]
	v_exp_f32_e32 v106, v106
	v_exp_f32_e32 v107, v107
	v_exp_f32_e32 v108, v108
	v_exp_f32_e32 v109, v109
	ds_read_b64 v[166:167], v214 offset:1088
	ds_read_b64 v[168:169], v214 offset:1120
	ds_read_b64 v[170:171], v215 offset:1344
	ds_read_b64 v[172:173], v215 offset:1376
	ds_read_b64 v[174:175], v216 offset:1600
	ds_read_b64 v[176:177], v216 offset:1632
	ds_read_b64 v[178:179], v217 offset:1088
	ds_read_b64 v[180:181], v217 offset:1120
	v_cvt_pk_bf16_f32 v186, v98, v99
	v_cvt_pk_bf16_f32 v187, v100, v101
	v_cvt_pk_bf16_f32 v188, v102, v103
	v_cvt_pk_bf16_f32 v189, v104, v105
	v_cvt_pk_bf16_f32 v190, v126, v127
	v_cvt_pk_bf16_f32 v191, v128, v129
	v_cvt_pk_bf16_f32 v192, v114, v115
	v_cvt_pk_bf16_f32 v193, v116, v117
	v_cvt_pk_bf16_f32 v194, v118, v119
	v_cvt_pk_bf16_f32 v195, v120, v121
	v_cvt_pk_bf16_f32 v196, v122, v123
	v_cvt_pk_bf16_f32 v197, v124, v125
	v_cvt_pk_bf16_f32 v182, v110, v111
	v_cvt_pk_bf16_f32 v183, v112, v113
	v_cvt_pk_bf16_f32 v184, v106, v107
	v_cvt_pk_bf16_f32 v185, v108, v109
	s_waitcnt lgkmcnt(14)
	v_mfma_f32_16x16x32_bf16 v[58:61], v[198:201], v[186:189], v[58:61]
	v_add_f32_e32 v0, 0, v98
	v_add_f32_e32 v2, 0, v126
	v_mfma_f32_16x16x32_bf16 v[42:45], v[198:201], v[190:193], v[42:45]
	v_add_f32_e32 v0, v99, v0
	v_add_f32_e32 v2, v127, v2
	s_waitcnt lgkmcnt(12)
	v_mfma_f32_16x16x32_bf16 v[54:57], v[202:205], v[186:189], v[54:57]
	v_add_f32_e32 v0, v100, v0
	v_add_f32_e32 v2, v128, v2
	v_mfma_f32_16x16x32_bf16 v[38:41], v[202:205], v[190:193], v[38:41]
	v_add_f32_e32 v0, v101, v0
	v_add_f32_e32 v2, v129, v2
	s_waitcnt lgkmcnt(10)
	v_mfma_f32_16x16x32_bf16 v[50:53], v[206:209], v[186:189], v[50:53]
	v_add_f32_e32 v0, v102, v0
	v_add_f32_e32 v2, v114, v2
	v_mfma_f32_16x16x32_bf16 v[34:37], v[206:209], v[190:193], v[34:37]
	v_add_f32_e32 v0, v103, v0
	v_add_f32_e32 v2, v115, v2
	s_waitcnt lgkmcnt(8)
	v_mfma_f32_16x16x32_bf16 v[46:49], v[210:213], v[186:189], v[46:49]
	v_add_f32_e32 v0, v104, v0
	v_add_f32_e32 v2, v116, v2
	v_mfma_f32_16x16x32_bf16 v[30:33], v[210:213], v[190:193], v[30:33]
	v_add_f32_e32 v0, v105, v0
	v_add_f32_e32 v2, v117, v2
	s_waitcnt lgkmcnt(6)
	v_mfma_f32_16x16x32_bf16 v[58:61], v[166:169], v[194:197], v[58:61]
	v_add_f32_e32 v0, v118, v0
	v_add_f32_e32 v2, v110, v2
	v_mfma_f32_16x16x32_bf16 v[42:45], v[166:169], v[182:185], v[42:45]
	v_add_f32_e32 v0, v119, v0
	v_add_f32_e32 v2, v111, v2
	s_waitcnt lgkmcnt(4)
	v_mfma_f32_16x16x32_bf16 v[54:57], v[170:173], v[194:197], v[54:57]
	v_add_f32_e32 v0, v120, v0
	v_add_f32_e32 v2, v112, v2
	v_mfma_f32_16x16x32_bf16 v[38:41], v[170:173], v[182:185], v[38:41]
	v_add_f32_e32 v0, v121, v0
	v_add_f32_e32 v2, v113, v2
	s_waitcnt lgkmcnt(2)
	v_mfma_f32_16x16x32_bf16 v[50:53], v[174:177], v[194:197], v[50:53]
	v_add_f32_e32 v0, v122, v0
	v_add_f32_e32 v2, v106, v2
	v_mfma_f32_16x16x32_bf16 v[34:37], v[174:177], v[182:185], v[34:37]
	v_add_f32_e32 v0, v123, v0
	v_add_f32_e32 v2, v107, v2
	s_waitcnt lgkmcnt(0)
	v_mfma_f32_16x16x32_bf16 v[46:49], v[178:181], v[194:197], v[46:49]
	v_add_f32_e32 v0, v124, v0
	v_add_f32_e32 v2, v108, v2
	v_mfma_f32_16x16x32_bf16 v[30:33], v[178:181], v[182:185], v[30:33]
	v_add_f32_e32 v0, v125, v0
	v_add_f32_e32 v2, v109, v2
	v_add_f32_e32 v163, v163, v0
	v_add_f32_e32 v162, v162, v2
	s_mov_b32 s32, 1
	s_branch .LBB0_888
; DI f32x4 mfma16(bf16x8 a, bf16x8 b, f32x4 c) { return __builtin_amdgcn_mfma_f32_16x16x32_bf16(a, b, c, 0, 0, 0); }
; DI void flash_s3(const u16* sK, const bf16x8 (&qf)[2][2], float si0, float si1, f32x4 (&s)[2][4], int lane) {
;   const int l15 = lane & 15, lg = lane >> 4;
;   bf16x8 kf[4][2];
; #pragma unroll
;   for (int kt = 0; kt < 4; ++kt)
; #pragma unroll
;     for (int ks = 0; ks < 2; ++ks) kf[kt][ks] = *(const bf16x8*)(sK + (16 * kt + l15) * 72 + ks * 32 + lg * 8);
; #pragma unroll
;   for (int qt = 0; qt < 2; ++qt) {
;     const float si = qt ? si1 : si0;
; #pragma unroll
;     for (int kt = 0; kt < 4; ++kt) {
;       s[qt][kt] = f32x4{si, si, si, si};
; #pragma unroll
;       for (int ks = 0; ks < 2; ++ks) s[qt][kt] = mfma16(kf[kt][ks], qf[qt][ks], s[qt][kt]);
;     }
;   }
; }
; template <bool MASKED, class MaskF>
; DI void flash_pv3(const u16* sV, const f32x4 (&s)[2][4], f32x4 (&O)[2][4], float (&l)[2], MaskF ok, int lane) {
;   const int l15 = lane & 15, lg = lane >> 4;
;   union PFrag { unsigned u[4]; bf16x8 v; };
;   PFrag pf[2][2];
; #pragma unroll
;   for (int qt = 0; qt < 2; ++qt) {
;     float pr[4][4];
;     float rs = 0.f;
; #pragma unroll
;     for (int kt = 0; kt < 4; ++kt)
; #pragma unroll
;       for (int i = 0; i < 4; ++i) {
;         float pv = __builtin_amdgcn_exp2f(s[qt][kt][i]);
;         if (MASKED) pv = ok(kt, i) ? pv : 0.f;
;         pr[kt][i] = pv;
;         rs += pv;
;       }
;     l[qt] += rs;
; #pragma unroll
;     for (int ks2 = 0; ks2 < 2; ++ks2) {
;       pf[qt][ks2].u[0] = pk2(pr[2 * ks2][0], pr[2 * ks2][1]);
;       pf[qt][ks2].u[1] = pk2(pr[2 * ks2][2], pr[2 * ks2][3]);
;       pf[qt][ks2].u[2] = pk2(pr[2 * ks2 + 1][0], pr[2 * ks2 + 1][1]);
;       pf[qt][ks2].u[3] = pk2(pr[2 * ks2 + 1][2], pr[2 * ks2 + 1][3]);
;     }
;   }
; #pragma unroll
;   for (int ks2 = 0; ks2 < 2; ++ks2) {
; #pragma unroll
;     for (int dt = 0; dt < 4; ++dt) {
;       union { uint2 h[2]; bf16x8 v; } vf;
;       vf.h[0] = *(const uint2*)(sV + (16 * dt + l15) * 72 + 32 * ks2 + 4 * lg);
;       vf.h[1] = *(const uint2*)(sV + (16 * dt + l15) * 72 + 32 * ks2 + 16 + 4 * lg);
;       O[0][dt] = mfma16(vf.v, pf[0][ks2].v, O[0][dt]);
;       O[1][dt] = mfma16(vf.v, pf[1][ks2].v, O[1][dt]);
;     }
;   }
.Lmy_selC_fastB:
	s_barrier
	v_lshrrev_b64 v[186:187], s42, v[20:21]
	v_lshrrev_b64 v[2:3], s42, v[22:23]
	s_cmp_lt_u32 s42, 64
	s_cselect_b64 s[36:37], -1, 0
	v_cndmask_b32_e64 v0, v2, v186, s[36:37]
	v_and_b32_e32 v0, 1, v0
	s_mul_i32 s36, s44, 0x4800
	v_cmp_eq_u32_e32 vcc, 1, v0
	v_add_u32_e32 v0, s36, v158
	v_lshl_add_u32 v2, v28, 1, v0
	ds_read_b128 v[126:129], v2
	ds_read_b128 v[114:117], v2 offset:64
	s_cmp_eq_u32 s42, s33
	ds_read_b128 v[110:113], v2 offset:2304
	ds_read_b128 v[106:109], v2 offset:2368
	s_cselect_b64 s[36:37], -1, 0
	s_or_b64 s[36:37], vcc, s[36:37]
	v_cndmask_b32_e64 v122, v148, -v29, s[36:37]
	v_lshl_add_u32 v0, v164, 1, v0
	v_cndmask_b32_e64 v182, v148, -v161, s[36:37]
	ds_read_b128 v[166:169], v2 offset:4608
	ds_read_b128 v[170:173], v2 offset:4672
	ds_read_b128 v[174:177], v0
	ds_read_b128 v[178:181], v0 offset:64
	v_mov_b32_e32 v123, v122
	v_mov_b32_e32 v124, v122
	v_mov_b32_e32 v125, v122
	v_mov_b32_e32 v183, v182
	v_mov_b32_e32 v184, v182
	v_mov_b32_e32 v185, v182
	s_mulk_i32 s45, 0x4800
	v_lshlrev_b32_e32 v160, 1, v28
	v_lshlrev_b32_e32 v3, 1, v164
	s_add_i32 s40, s45, 32
	v_add3_u32 v198, s40, v160, v159
	v_add3_u32 v206, s40, v3, v159
	v_add_u32_e32 v214, 0x2000, v198
	v_add_u32_e32 v215, 0x2800, v198
	v_add_u32_e32 v216, 0x3000, v198
	v_add_u32_e32 v217, 0x2000, v206
	v_exp_f32_e32 v66, v66
	v_exp_f32_e32 v67, v67
	v_exp_f32_e32 v68, v68
	v_exp_f32_e32 v69, v69
	v_exp_f32_e32 v70, v70
	v_exp_f32_e32 v71, v71
	s_waitcnt lgkmcnt(7)
	v_mfma_f32_16x16x32_bf16 v[98:101], v[126:129], v[4:7], v[122:125]
	v_exp_f32_e32 v72, v72
	v_mfma_f32_16x16x32_bf16 v[126:129], v[126:129], v[12:15], v[182:185]
	v_exp_f32_e32 v73, v73
	s_waitcnt lgkmcnt(6)
	v_mfma_f32_16x16x32_bf16 v[98:101], v[114:117], v[8:11], v[98:101]
	ds_read_b64 v[198:199], v214 offset:1024
	ds_read_b64 v[200:201], v214 offset:1056
	ds_read_b64 v[202:203], v215 offset:1280
	ds_read_b64 v[204:205], v215 offset:1312
	ds_read_b64 v[206:207], v216 offset:1536
	ds_read_b64 v[208:209], v216 offset:1568
	ds_read_b64 v[210:211], v217 offset:1024
	ds_read_b64 v[212:213], v217 offset:1056
	v_exp_f32_e32 v74, v74
	v_exp_f32_e32 v75, v75
	s_waitcnt lgkmcnt(13)
	v_mfma_f32_16x16x32_bf16 v[102:105], v[110:113], v[4:7], v[122:125]
	v_exp_f32_e32 v76, v76
	v_mfma_f32_16x16x32_bf16 v[126:129], v[114:117], v[16:19], v[126:129]
	v_exp_f32_e32 v77, v77
	v_mfma_f32_16x16x32_bf16 v[114:117], v[110:113], v[12:15], v[182:185]
	v_exp_f32_e32 v78, v78
	v_exp_f32_e32 v79, v79
	s_waitcnt lgkmcnt(12)
	v_mfma_f32_16x16x32_bf16 v[102:105], v[106:109], v[8:11], v[102:105]
	v_exp_f32_e32 v80, v80
	v_exp_f32_e32 v81, v81
	s_waitcnt lgkmcnt(11)
	v_mfma_f32_16x16x32_bf16 v[118:121], v[166:169], v[4:7], v[122:125]
	v_exp_f32_e32 v82, v82
	v_exp_f32_e32 v83, v83
	s_waitcnt lgkmcnt(9)
	v_mfma_f32_16x16x32_bf16 v[122:125], v[174:177], v[4:7], v[122:125]
	v_exp_f32_e32 v84, v84
	v_mfma_f32_16x16x32_bf16 v[114:117], v[106:109], v[16:19], v[114:117]
	v_exp_f32_e32 v85, v85
	v_mfma_f32_16x16x32_bf16 v[110:113], v[166:169], v[12:15], v[182:185]
	v_exp_f32_e32 v86, v86
	v_mfma_f32_16x16x32_bf16 v[106:109], v[174:177], v[12:15], v[182:185]
	v_exp_f32_e32 v87, v87
	v_mfma_f32_16x16x32_bf16 v[118:121], v[170:173], v[8:11], v[118:121]
	v_exp_f32_e32 v88, v88
	v_exp_f32_e32 v89, v89
	s_waitcnt lgkmcnt(8)
	v_mfma_f32_16x16x32_bf16 v[122:125], v[178:181], v[8:11], v[122:125]
	v_exp_f32_e32 v90, v90
	v_exp_f32_e32 v91, v91
	v_mfma_f32_16x16x32_bf16 v[110:113], v[170:173], v[16:19], v[110:113]
	v_exp_f32_e32 v92, v92
	v_exp_f32_e32 v93, v93
	v_mfma_f32_16x16x32_bf16 v[106:109], v[178:181], v[16:19], v[106:109]
	v_exp_f32_e32 v94, v94
	v_exp_f32_e32 v95, v95
	v_exp_f32_e32 v96, v96
	v_exp_f32_e32 v97, v97
	ds_read_b64 v[166:167], v214 offset:1088
	ds_read_b64 v[168:169], v214 offset:1120
	ds_read_b64 v[170:171], v215 offset:1344
	ds_read_b64 v[172:173], v215 offset:1376
	ds_read_b64 v[174:175], v216 offset:1600
	ds_read_b64 v[176:177], v216 offset:1632
	ds_read_b64 v[178:179], v217 offset:1088
	ds_read_b64 v[180:181], v217 offset:1120
	v_cvt_pk_bf16_f32 v186, v66, v67
	v_cvt_pk_bf16_f32 v187, v68, v69
	v_cvt_pk_bf16_f32 v188, v70, v71
	v_cvt_pk_bf16_f32 v189, v72, v73
	v_cvt_pk_bf16_f32 v190, v82, v83
	v_cvt_pk_bf16_f32 v191, v84, v85
	v_cvt_pk_bf16_f32 v192, v86, v87
	v_cvt_pk_bf16_f32 v193, v88, v89
	v_cvt_pk_bf16_f32 v194, v74, v75
	v_cvt_pk_bf16_f32 v195, v76, v77
	v_cvt_pk_bf16_f32 v196, v78, v79
	v_cvt_pk_bf16_f32 v197, v80, v81
	v_cvt_pk_bf16_f32 v182, v90, v91
	v_cvt_pk_bf16_f32 v183, v92, v93
	v_cvt_pk_bf16_f32 v184, v94, v95
	v_cvt_pk_bf16_f32 v185, v96, v97
	s_waitcnt lgkmcnt(14)
	v_mfma_f32_16x16x32_bf16 v[58:61], v[198:201], v[186:189], v[58:61]
	v_add_f32_e32 v0, 0, v66
	v_add_f32_e32 v2, 0, v82
	v_mfma_f32_16x16x32_bf16 v[42:45], v[198:201], v[190:193], v[42:45]
	v_add_f32_e32 v0, v67, v0
	v_add_f32_e32 v2, v83, v2
	s_waitcnt lgkmcnt(12)
	v_mfma_f32_16x16x32_bf16 v[54:57], v[202:205], v[186:189], v[54:57]
	v_add_f32_e32 v0, v68, v0
	v_add_f32_e32 v2, v84, v2
	v_mfma_f32_16x16x32_bf16 v[38:41], v[202:205], v[190:193], v[38:41]
	v_add_f32_e32 v0, v69, v0
	v_add_f32_e32 v2, v85, v2
	s_waitcnt lgkmcnt(10)
	v_mfma_f32_16x16x32_bf16 v[50:53], v[206:209], v[186:189], v[50:53]
	v_add_f32_e32 v0, v70, v0
	v_add_f32_e32 v2, v86, v2
	v_mfma_f32_16x16x32_bf16 v[34:37], v[206:209], v[190:193], v[34:37]
	v_add_f32_e32 v0, v71, v0
	v_add_f32_e32 v2, v87, v2
	s_waitcnt lgkmcnt(8)
	v_mfma_f32_16x16x32_bf16 v[46:49], v[210:213], v[186:189], v[46:49]
	v_add_f32_e32 v0, v72, v0
	v_add_f32_e32 v2, v88, v2
	v_mfma_f32_16x16x32_bf16 v[30:33], v[210:213], v[190:193], v[30:33]
	v_add_f32_e32 v0, v73, v0
	v_add_f32_e32 v2, v89, v2
	s_waitcnt lgkmcnt(6)
	v_mfma_f32_16x16x32_bf16 v[58:61], v[166:169], v[194:197], v[58:61]
	v_add_f32_e32 v0, v74, v0
	v_add_f32_e32 v2, v90, v2
	v_mfma_f32_16x16x32_bf16 v[42:45], v[166:169], v[182:185], v[42:45]
	v_add_f32_e32 v0, v75, v0
	v_add_f32_e32 v2, v91, v2
	s_waitcnt lgkmcnt(4)
	v_mfma_f32_16x16x32_bf16 v[54:57], v[170:173], v[194:197], v[54:57]
	v_add_f32_e32 v0, v76, v0
	v_add_f32_e32 v2, v92, v2
	v_mfma_f32_16x16x32_bf16 v[38:41], v[170:173], v[182:185], v[38:41]
	v_add_f32_e32 v0, v77, v0
	v_add_f32_e32 v2, v93, v2
	s_waitcnt lgkmcnt(2)
	v_mfma_f32_16x16x32_bf16 v[50:53], v[174:177], v[194:197], v[50:53]
	v_add_f32_e32 v0, v78, v0
	v_add_f32_e32 v2, v94, v2
	v_mfma_f32_16x16x32_bf16 v[34:37], v[174:177], v[182:185], v[34:37]
	v_add_f32_e32 v0, v79, v0
	v_add_f32_e32 v2, v95, v2
	s_waitcnt lgkmcnt(0)
	v_mfma_f32_16x16x32_bf16 v[46:49], v[178:181], v[194:197], v[46:49]
	v_add_f32_e32 v0, v80, v0
	v_add_f32_e32 v2, v96, v2
	v_mfma_f32_16x16x32_bf16 v[30:33], v[178:181], v[182:185], v[30:33]
	v_add_f32_e32 v0, v81, v0
	v_add_f32_e32 v2, v97, v2
	v_add_f32_e32 v163, v163, v0
	v_add_f32_e32 v162, v162, v2
	s_mov_b32 s32, 0
	s_branch .LBB0_888
